# gdn_prep stage B: fragment reads of a tile task issued together with counted waits, sgc/sbeta row scalars read once up front; nsa_main variant A: counted lgkmcnt for the first S MFMAs (on top of v11)
# speedup vs baseline: 1.0034x; 1.0034x over previous
; #define MFMA16(a, b, c) __builtin_amdgcn_mfma_f32_16x16x32_bf16((a), (b), (c), 0, 0, 0)
; template <int STRIP> __device__ __forceinline__ void ph_gdn_prep_fast(const bf16* __restrict__ proj, const float* __restrict__ small, const float* __restrict__ conv_w, const float* __restrict__ a_log, const float* __restrict__ dt_bias, ...
;     ...
;               if (tj <= ti) {
;                   const unsigned char* xa = L + (isA ? GP_Q : GP_K) + ((16 * ti + r16) * GP_STR + 8 * a) * 2;
;                   const unsigned char* xb = L + GP_K + ((16 * tj + r16) * GP_STR + 8 * a) * 2;
; #pragma unroll
;                   for (int s = 0; s < 4; ++s) acc = MFMA16(__builtin_bit_cast(bf16x8, *(const u32x4*)(xa + 64 * s)), __builtin_bit_cast(bf16x8, *(const u32x4*)(xb + 64 * s)), acc);
;               }
;               const int j = 16 * tj + r16; const float gj = sgc[j];
; #pragma unroll
;               for (int reg = 0; reg < 4; ++reg) { const int i = 16 * ti + 4 * a + reg; const float dec = __expf(sgc[i] - gj);
;                   if (!isA) { ((float*)(L + GP_L))[i * GP_LSTR + j] = j < i ? sbeta[i] * acc[reg] * dec : 0.f; }
.LBB0_1273:
	s_andn2_saveexec_b64 s[6:7], s[12:13]
	v_add_u32_e32 v4, -10, v4
	v_lshrrev_b32_e32 v2, 2, v4
	v_and_b32_e32 v4, 3, v4
	s_or_b64 exec, exec, s[6:7]
	v_mov_b32_e32 v5, 0x11500
	v_cndmask_b32_e64 v5, 0, v5, s[4:5]
	v_add_u32_e32 v10, 0, v5
	v_cmp_le_i32_e64 s[6:7], v4, v2
	v_lshlrev_b32_e32 v2, 4, v2
	v_lshlrev_b32_e32 v12, 4, v4
	s_and_saveexec_b64 s[2:3], s[6:7]
	s_xor_b64 s[6:7], exec, s[2:3]
	s_cbranch_execz .LBB0_1277
	v_or_b32_e32 v6, v2, v16
	v_mul_lo_u32 v6, v6, s49
	v_lshlrev_b32_e32 v12, 4, v4
	v_cndmask_b32_e64 v5, v236, 0, s[0:1]
	v_add_lshl_u32 v6, v6, v8, 1
	v_or_b32_e32 v19, v12, v16
	v_add3_u32 v13, v10, v5, v6
	v_mad_u64_u32 v[4:5], s[0:1], v19, s49, v[8:9]
	v_lshl_add_u32 v14, v4, 1, v10
	ds_read_b128 v[4:7], v13
	ds_read_b128 v[20:23], v14 offset:17408
	ds_read_b128 v[40:43], v13 offset:64
	ds_read_b128 v[44:47], v14 offset:17472
	ds_read_b128 v[48:51], v13 offset:128
	ds_read_b128 v[52:55], v14 offset:17536
	ds_read_b128 v[56:59], v13 offset:192
	ds_read_b128 v[60:63], v14 offset:17600
	s_waitcnt lgkmcnt(6)
	v_mfma_f32_16x16x32_bf16 v[4:7], v[4:7], v[20:23], 0
	s_waitcnt lgkmcnt(4)
	v_mfma_f32_16x16x32_bf16 v[4:7], v[40:43], v[44:47], v[4:7]
	s_waitcnt lgkmcnt(2)
	v_mfma_f32_16x16x32_bf16 v[4:7], v[48:51], v[52:55], v[4:7]
	s_waitcnt lgkmcnt(0)
	v_mfma_f32_16x16x32_bf16 v[4:7], v[56:59], v[60:63], v[4:7]
.LBB0_1277:
	s_andn2_saveexec_b64 s[0:1], s[6:7]
	v_or_b32_e32 v19, v12, v16
	s_nop 5
	v_mov_b32_e32 v4, 0
	v_mov_b32_e32 v5, 0
	v_mov_b32_e32 v6, 0
	v_mov_b32_e32 v7, 0
	s_or_b64 exec, exec, s[0:1]
	v_add_u32_e32 v21, 0x11000, v10
	v_lshlrev_b32_e32 v13, 2, v19
	v_or_b32_e32 v2, v2, v17
	v_add_u32_e32 v20, 0x11100, v10
	v_add_u32_e32 v14, v21, v13
	v_add_u32_e32 v10, v10, v13
	v_lshl_add_u32 v13, v2, 2, v21
	v_lshl_add_u32 v36, v2, 2, v20
	ds_read_b32 v22, v14
	ds_read_b32 v28, v13 offset:4
	ds_read_b32 v29, v13 offset:8
	ds_read_b32 v30, v13 offset:12
	ds_read_b32 v31, v36
	ds_read_b32 v32, v36 offset:4
	ds_read_b32 v33, v36 offset:8
	ds_read_b32 v34, v36 offset:12
	ds_read_b32 v13, v13
	s_waitcnt lgkmcnt(0)
	v_sub_f32_e32 v13, v13, v22
	v_mul_f32_e32 v13, 0x3fb8aa3b, v13
	v_exp_f32_e32 v14, v13
	s_and_saveexec_b64 s[0:1], vcc
	s_xor_b64 s[6:7], exec, s[0:1]
	s_cbranch_execz .LBB0_1283
	v_cmp_lt_i32_e64 s[0:1], v19, v2
	v_mov_b32_e32 v13, 0
	s_and_saveexec_b64 s[12:13], s[0:1]
	s_cbranch_execz .LBB0_1282
	v_mov_b32_e32 v13, v31
	v_mul_f32_e32 v4, v4, v13
	v_mul_f32_e32 v13, v14, v4

; template <int STRIP> __device__ __forceinline__ void ph_gdn_prep_fast(const bf16* __restrict__ proj, const float* __restrict__ small, const float* __restrict__ conv_w, const float* __restrict__ a_log, const float* __restrict__ dt_bias, ...
;     ...
;               const int j = 16 * tj + r16; const float gj = sgc[j];
; #pragma unroll
;               for (int reg = 0; reg < 4; ++reg) { const int i = 16 * ti + 4 * a + reg; const float dec = __expf(sgc[i] - gj);
;                   if (!isA) { ((float*)(L + GP_L))[i * GP_LSTR + j] = j < i ? sbeta[i] * acc[reg] * dec : 0.f; }
.LBB0_1285:
	s_or_b64 exec, exec, s[6:7]
	v_or_b32_e32 v14, 1, v2
	v_mov_b32_e32 v4, v28
	v_sub_f32_e32 v4, v4, v22
	v_mul_f32_e32 v4, 0x3fb8aa3b, v4
	v_exp_f32_e32 v4, v4
	s_and_saveexec_b64 s[0:1], vcc
	s_xor_b64 s[4:5], exec, s[0:1]
	s_cbranch_execz .LBB0_1289
	v_cmp_le_i32_e64 s[0:1], v19, v2
	v_mov_b32_e32 v15, 0
	s_and_saveexec_b64 s[6:7], s[0:1]
	s_cbranch_execz .LBB0_1288
	v_mov_b32_e32 v15, v32
	v_mul_f32_e32 v5, v5, v15
	v_mul_f32_e32 v15, v4, v5

; template <int STRIP> __device__ __forceinline__ void ph_gdn_prep_fast(const bf16* __restrict__ proj, const float* __restrict__ small, const float* __restrict__ conv_w, const float* __restrict__ a_log, const float* __restrict__ dt_bias, ...
;     ...
;               const int j = 16 * tj + r16; const float gj = sgc[j];
; #pragma unroll
;               for (int reg = 0; reg < 4; ++reg) { const int i = 16 * ti + 4 * a + reg; const float dec = __expf(sgc[i] - gj);
;                   if (!isA) { ((float*)(L + GP_L))[i * GP_LSTR + j] = j < i ? sbeta[i] * acc[reg] * dec : 0.f; }
.LBB0_1291:
	s_or_b64 exec, exec, s[4:5]
	v_or_b32_e32 v4, 2, v2
	v_mov_b32_e32 v5, v29
	v_sub_f32_e32 v5, v5, v22
	v_mul_f32_e32 v5, 0x3fb8aa3b, v5
	v_exp_f32_e32 v14, v5
	s_and_saveexec_b64 s[0:1], vcc
	s_xor_b64 s[4:5], exec, s[0:1]
	s_cbranch_execz .LBB0_1295
	v_cmp_lt_i32_e64 s[0:1], v19, v4
	v_mov_b32_e32 v5, 0
	s_and_saveexec_b64 s[6:7], s[0:1]
	s_cbranch_execz .LBB0_1294
	v_mov_b32_e32 v5, v33
	v_mul_f32_e32 v5, v6, v5
	v_mul_f32_e32 v5, v14, v5

; template <int STRIP> __device__ __forceinline__ void ph_gdn_prep_fast(const bf16* __restrict__ proj, const float* __restrict__ small, const float* __restrict__ conv_w, const float* __restrict__ a_log, const float* __restrict__ dt_bias, ...
;     ...
;               const int j = 16 * tj + r16; const float gj = sgc[j];
; #pragma unroll
;               for (int reg = 0; reg < 4; ++reg) { const int i = 16 * ti + 4 * a + reg; const float dec = __expf(sgc[i] - gj);
;                   if (!isA) { ((float*)(L + GP_L))[i * GP_LSTR + j] = j < i ? sbeta[i] * acc[reg] * dec : 0.f; }
.LBB0_1297:
	s_or_b64 exec, exec, s[4:5]
	v_or_b32_e32 v2, 3, v2
	v_mov_b32_e32 v4, v30
	v_sub_f32_e32 v4, v4, v22
	v_mul_f32_e32 v4, 0x3fb8aa3b, v4
	v_exp_f32_e32 v4, v4
	s_and_saveexec_b64 s[0:1], vcc
	s_xor_b64 s[0:1], exec, s[0:1]
	s_cbranch_execz .LBB0_1301
	v_cmp_lt_i32_e32 vcc, v19, v2
	v_mov_b32_e32 v5, 0
	s_and_saveexec_b64 s[4:5], vcc
	s_cbranch_execz .LBB0_1300
	v_mov_b32_e32 v5, v34
	v_mul_f32_e32 v5, v7, v5
	v_mul_f32_e32 v5, v4, v5

; #define MFMA32(a, b, c) __builtin_amdgcn_mfma_f32_32x32x16_bf16((a), (b), (c), 0, 0, 0)
; template <int MODE, int KIND> __device__ __forceinline__ void attn_tile(const LAS unsigned char* fq, const LAS unsigned char* tb, float msk, int dlim, const bf16x8 (&qf)[8], f32x16 (&O)[4], float& lsum) {
;     ...
;     u32x4 fa[4], fb[4]; f32x16 S0, S1; bf16x8 pb0[2], pb1[2];
;     ATT_SINIT(S0, 0);
; #pragma unroll
;     for (int s = 0; s < 4; ++s) fa[s] = ATT_KF(0, s);
;     ATT_SB();
; #pragma unroll
;     for (int s = 0; s < 4; ++s) fb[s] = ATT_KF(0, 4 + s);
; #pragma unroll
;     for (int s = 0; s < 4; ++s) S0 = MFMA32(ATT_BF(fa[s]), qf[s], S0);
;     ATT_SB();
; #pragma unroll
;     for (int s = 0; s < 4; ++s) fa[s] = ATT_KF(1, s);
;     ATT_SINIT(S1, 1);
; #pragma unroll
;     for (int s = 0; s < 4; ++s) S0 = MFMA32(ATT_BF(fb[s]), qf[4 + s], S0);
;     ATT_SB();
; #pragma unroll
;     for (int s = 0; s < 4; ++s) fb[s] = ATT_KF(1, 4 + s);
; #pragma unroll
;     for (int s = 0; s < 4; ++s) S1 = MFMA32(ATT_BF(fa[s]), qf[s], S1);
;     ATT_SB();
;     fa[0] = ATT_VF(0, 0); fa[1] = ATT_VF(0, 1); fa[2] = ATT_VF(1, 0); fa[3] = ATT_VF(1, 1);
; #pragma unroll
;     for (int s = 0; s < 4; ++s) S1 = MFMA32(ATT_BF(fb[s]), qf[4 + s], S1);
;     ATT_EXP(S0, 0, pb0);
;     ATT_SB();
;     fb[0] = ATT_VF(2, 0); fb[1] = ATT_VF(2, 1); fb[2] = ATT_VF(3, 0); fb[3] = ATT_VF(3, 1);
;     O[0] = MFMA32(ATT_BF(fa[0]), pb0[0], O[0]); O[0] = MFMA32(ATT_BF(fa[1]), pb0[1], O[0]); O[1] = MFMA32(ATT_BF(fa[2]), pb0[0], O[1]); O[1] = MFMA32(ATT_BF(fa[3]), pb0[1], O[1]);
;     ATT_EXP(S1, 1, pb1);
;     ATT_SB();
;     fa[0] = ATT_VF(0, 2); fa[1] = ATT_VF(0, 3); fa[2] = ATT_VF(1, 2); fa[3] = ATT_VF(1, 3);
;     O[2] = MFMA32(ATT_BF(fb[0]), pb0[0], O[2]); O[2] = MFMA32(ATT_BF(fb[1]), pb0[1], O[2]); O[3] = MFMA32(ATT_BF(fb[2]), pb0[0], O[3]); O[3] = MFMA32(ATT_BF(fb[3]), pb0[1], O[3]);
;     ATT_SB();
;     fb[0] = ATT_VF(2, 2); fb[1] = ATT_VF(2, 3); fb[2] = ATT_VF(3, 2); fb[3] = ATT_VF(3, 3);
;     O[0] = MFMA32(ATT_BF(fa[0]), pb1[0], O[0]); O[0] = MFMA32(ATT_BF(fa[1]), pb1[1], O[0]); O[1] = MFMA32(ATT_BF(fa[2]), pb1[0], O[1]); O[1] = MFMA32(ATT_BF(fa[3]), pb1[1], O[1]);
;     ATT_SB();
;     O[2] = MFMA32(ATT_BF(fb[0]), pb1[0], O[2]); O[2] = MFMA32(ATT_BF(fb[1]), pb1[1], O[2]); O[3] = MFMA32(ATT_BF(fb[2]), pb1[0], O[3]); O[3] = MFMA32(ATT_BF(fb[3]), pb1[1], O[3]);
.LBB0_1856:
	s_cmp_le_i32 s34, s62
	s_cselect_b64 s[12:13], -1, 0
	s_add_i32 s15, s34, 63
	s_cmp_ge_i32 s15, s19
	s_cselect_b64 s[26:27], -1, 0
	s_and_b64 s[12:13], s[12:13], s[26:27]
	s_andn2_b64 vcc, exec, s[12:13]
	s_cbranch_vccnz .LBB0_1866
	s_add_i32 s12, s35, 0xffffffa2
	v_lshl_add_u32 v2, s14, 15, v1
	s_cmpk_lt_i32 s12, 0x80
	s_mov_b64 s[12:13], -1
	s_cbranch_scc0 .LBB0_1859
	ds_read_b128 v[68:71], v183
	ds_read_b128 v[72:75], v183 offset:32
	ds_read_b128 v[76:79], v183 offset:64
	ds_read_b128 v[80:83], v183 offset:96
	ds_read_b128 v[84:87], v2
	ds_read_b128 v[88:91], v2 offset:1024
	ds_read_b128 v[92:95], v2 offset:2048
	ds_read_b128 v[96:99], v2 offset:3072
	ds_read_b128 v[108:111], v2 offset:4096
	ds_read_b128 v[112:115], v2 offset:5120
	ds_read_b128 v[116:119], v2 offset:6144
	ds_read_b128 v[120:123], v2 offset:7168
	s_waitcnt lgkmcnt(7)
	v_mfma_f32_32x32x16_bf16 v[68:83], v[84:87], v[132:135], v[68:83]
	ds_read_b128 v[124:127], v2 offset:8192
	ds_read_b128 v[128:131], v2 offset:9216
	ds_read_b128 v[164:167], v2 offset:10240
	ds_read_b128 v[168:171], v2 offset:11264
	s_waitcnt lgkmcnt(10)
	v_mfma_f32_32x32x16_bf16 v[68:83], v[88:91], v[136:139], v[68:83]
	s_waitcnt lgkmcnt(9)
	v_mfma_f32_32x32x16_bf16 v[68:83], v[92:95], v[140:143], v[68:83]
	s_waitcnt lgkmcnt(8)
	v_mfma_f32_32x32x16_bf16 v[68:83], v[96:99], v[144:147], v[68:83]
	ds_read_b128 v[92:95], v183 offset:128
	ds_read_b128 v[96:99], v183 offset:160
	ds_read_b128 v[100:103], v183 offset:192
	ds_read_b128 v[104:107], v183 offset:224
	s_waitcnt lgkmcnt(0)
	v_mfma_f32_32x32x16_bf16 v[92:107], v[124:127], v[132:135], v[92:107]
	v_mfma_f32_32x32x16_bf16 v[92:107], v[128:131], v[136:139], v[92:107]
	v_mfma_f32_32x32x16_bf16 v[68:83], v[108:111], v[148:151], v[68:83]
	v_mfma_f32_32x32x16_bf16 v[92:107], v[164:167], v[140:143], v[92:107]
	v_mfma_f32_32x32x16_bf16 v[68:83], v[112:115], v[152:155], v[68:83]
	ds_read_b128 v[84:87], v2 offset:12288
	ds_read_b128 v[88:91], v2 offset:13312
	ds_read_b128 v[108:111], v2 offset:14336
	ds_read_b128 v[112:115], v2 offset:15360
	v_mfma_f32_32x32x16_bf16 v[92:107], v[168:171], v[144:147], v[92:107]
	v_mfma_f32_32x32x16_bf16 v[68:83], v[116:119], v[156:159], v[68:83]
	s_waitcnt lgkmcnt(0)
	v_mfma_f32_32x32x16_bf16 v[92:107], v[84:87], v[148:151], v[92:107]
	ds_read_b128 v[116:119], v2 offset:16384
	ds_read_b128 v[124:127], v2 offset:17408
	ds_read_b128 v[128:131], v2 offset:20480
	ds_read_b128 v[164:167], v2 offset:21504
	v_mfma_f32_32x32x16_bf16 v[68:83], v[120:123], v[160:163], v[68:83]
	v_mfma_f32_32x32x16_bf16 v[92:107], v[88:91], v[152:155], v[92:107]
	s_nop 10
	v_exp_f32_e32 v68, v68
	v_exp_f32_e32 v69, v69
	v_exp_f32_e32 v70, v70
	v_exp_f32_e32 v71, v71
	v_exp_f32_e32 v72, v72
	v_add_f32_e32 v120, v197, v68
	v_exp_f32_e32 v73, v73
	v_mfma_f32_32x32x16_bf16 v[92:107], v[108:111], v[156:159], v[92:107]
	v_add_f32_e32 v120, v69, v120
	v_exp_f32_e32 v74, v74
	v_add_f32_e32 v120, v70, v120
	v_add_f32_e32 v120, v71, v120
	v_exp_f32_e32 v75, v75
	v_add_f32_e32 v120, v72, v120
	v_exp_f32_e32 v76, v76
	v_add_f32_e32 v120, v73, v120
	v_exp_f32_e32 v77, v77
	v_add_f32_e32 v120, v74, v120
	v_exp_f32_e32 v78, v78
	v_add_f32_e32 v120, v75, v120
	v_exp_f32_e32 v79, v79
	v_add_f32_e32 v84, v76, v120
	v_exp_f32_e32 v80, v80
	v_mfma_f32_32x32x16_bf16 v[92:107], v[112:115], v[160:163], v[92:107]
	v_add_f32_e32 v84, v77, v84
	v_exp_f32_e32 v81, v81
	v_add_f32_e32 v84, v78, v84
	v_exp_f32_e32 v82, v82
	v_add_f32_e32 v84, v79, v84
	v_exp_f32_e32 v83, v83
	v_add_f32_e32 v84, v80, v84
	v_add_f32_e32 v84, v81, v84
	v_add_f32_e32 v84, v82, v84
	v_add_f32_e32 v84, v83, v84
	v_cvt_pk_bf16_f32 v168, v68, v69
	v_cvt_pk_bf16_f32 v169, v70, v71
	v_cvt_pk_bf16_f32 v170, v72, v73
	v_cvt_pk_bf16_f32 v171, v74, v75
	v_cvt_pk_bf16_f32 v172, v76, v77
	v_cvt_pk_bf16_f32 v173, v78, v79
	v_cvt_pk_bf16_f32 v174, v80, v81
	v_cvt_pk_bf16_f32 v175, v82, v83
	v_exp_f32_e32 v108, v92
	v_exp_f32_e32 v109, v93
	v_exp_f32_e32 v110, v94
	v_exp_f32_e32 v111, v95
	v_add_f32_e32 v84, v108, v84
	v_exp_f32_e32 v112, v96
	v_add_f32_e32 v84, v109, v84
	v_exp_f32_e32 v113, v97
	v_add_f32_e32 v84, v110, v84
	v_exp_f32_e32 v114, v98
	v_add_f32_e32 v84, v111, v84
	v_add_f32_e32 v84, v112, v84
	v_add_f32_e32 v84, v113, v84
	s_waitcnt lgkmcnt(0)
	v_mfma_f32_32x32x16_bf16 v[52:67], v[116:119], v[168:171], v[52:67]
	v_exp_f32_e32 v115, v99
	v_add_f32_e32 v116, v114, v84
	v_exp_f32_e32 v100, v100
	v_exp_f32_e32 v101, v101
	v_exp_f32_e32 v102, v102
	v_add_f32_e32 v116, v115, v116
	v_exp_f32_e32 v103, v103
	v_mfma_f32_32x32x16_bf16 v[36:51], v[128:131], v[168:171], v[36:51]
	v_add_f32_e32 v116, v100, v116
	v_exp_f32_e32 v104, v104
	v_add_f32_e32 v116, v101, v116
	v_exp_f32_e32 v105, v105
	v_add_f32_e32 v116, v102, v116
	v_exp_f32_e32 v106, v106
	ds_read_b128 v[120:123], v2 offset:24576
	ds_read_b128 v[176:179], v2 offset:25600
	v_mfma_f32_32x32x16_bf16 v[52:67], v[124:127], v[172:175], v[52:67]
	ds_read_b128 v[198:201], v2 offset:28672
	ds_read_b128 v[202:205], v2 offset:29696
	v_add_f32_e32 v116, v103, v116
	v_exp_f32_e32 v107, v107
	v_add_f32_e32 v116, v104, v116
	v_add_f32_e32 v116, v105, v116
	v_add_f32_e32 v116, v106, v116
	v_add_f32_e32 v184, v107, v116
	v_mfma_f32_32x32x16_bf16 v[36:51], v[164:167], v[172:175], v[36:51]
	v_cvt_pk_bf16_f32 v164, v108, v109
	v_cvt_pk_bf16_f32 v165, v110, v111
	v_cvt_pk_bf16_f32 v166, v112, v113
	v_cvt_pk_bf16_f32 v167, v114, v115
	v_cvt_pk_bf16_f32 v206, v100, v101
	v_cvt_pk_bf16_f32 v207, v102, v103
	v_cvt_pk_bf16_f32 v208, v104, v105
	v_cvt_pk_bf16_f32 v209, v106, v107
	s_waitcnt lgkmcnt(0)
	v_mfma_f32_32x32x16_bf16 v[20:35], v[120:123], v[168:171], v[20:35]
	v_mfma_f32_32x32x16_bf16 v[4:19], v[198:201], v[168:171], v[4:19]
	v_mfma_f32_32x32x16_bf16 v[20:35], v[176:179], v[172:175], v[20:35]
	ds_read_b128 v[168:171], v2 offset:18432
	ds_read_b128 v[176:179], v2 offset:19456
	ds_read_b128 v[198:201], v2 offset:22528
	ds_read_b128 v[210:213], v2 offset:23552
	v_mfma_f32_32x32x16_bf16 v[4:19], v[202:205], v[172:175], v[4:19]
	s_waitcnt lgkmcnt(0)
	v_mfma_f32_32x32x16_bf16 v[52:67], v[168:171], v[164:167], v[52:67]
	v_mfma_f32_32x32x16_bf16 v[36:51], v[198:201], v[164:167], v[36:51]
	v_mfma_f32_32x32x16_bf16 v[52:67], v[176:179], v[206:209], v[52:67]
	ds_read_b128 v[168:171], v2 offset:26624
	ds_read_b128 v[172:175], v2 offset:27648
	ds_read_b128 v[176:179], v2 offset:30720
	ds_read_b128 v[198:201], v2 offset:31744
	v_mfma_f32_32x32x16_bf16 v[36:51], v[210:213], v[206:209], v[36:51]
	s_waitcnt lgkmcnt(0)
	v_mfma_f32_32x32x16_bf16 v[20:35], v[168:171], v[164:167], v[20:35]
	v_mfma_f32_32x32x16_bf16 v[4:19], v[176:179], v[164:167], v[4:19]
	v_mfma_f32_32x32x16_bf16 v[20:35], v[172:175], v[206:209], v[20:35]
	v_mfma_f32_32x32x16_bf16 v[4:19], v[198:201], v[206:209], v[4:19]
	s_mov_b64 s[12:13], 0
